# G1: group A does POOL tile first and Z tile (needed only in M2) last, and arrives at barrier a inside its third unit: M1 starts after two rounds
# speedup vs baseline: 1.0441x; 1.0192x over previous
.LBB0_83:
	s_andn2_b64 vcc, exec, s[0:1]
	s_cbranch_vccnz .LBB0_310
	v_readlane_b32 s8, v252, 0
	v_readlane_b32 s9, v252, 1
	s_waitcnt lgkmcnt(0)
	s_load_dwordx2 s[22:23], s[8:9], 0xd8
	s_mul_i32 s0, s26, 0x1800000
	v_mov_b32_e32 v12, v0
	s_waitcnt lgkmcnt(0)
	s_add_u32 s0, s22, s0
	s_addc_u32 s1, s23, 0
	s_add_u32 s0, s0, 0x200000
	s_addc_u32 s1, s1, 0
	s_add_u32 s10, s22, 0x3200000
	s_addc_u32 s11, s23, 0
	s_lshl_b32 s34, s26, 17
	s_lshl_b64 s[4:5], s[34:35], 2
	s_add_u32 s4, s22, s4
	s_addc_u32 s5, s23, s5
	s_add_u32 s6, s4, 0x10000
	s_addc_u32 s7, s5, 0
	v_readlane_b32 s4, v252, 13
	v_readlane_b32 s5, v252, 14
	s_andn2_b64 vcc, exec, s[4:5]
	v_readfirstlane_b32 s28, v12
	s_cbranch_vccnz .LBB0_198
	v_lshlrev_b32_e32 v1, 4, v12
	v_add_u32_e32 v2, 0x2000, v1
	v_ashrrev_i32_e32 v4, 31, v2
	v_lshrrev_b32_e32 v4, 22, v4
	v_add_u32_e32 v4, v2, v4
	v_ashrrev_i32_e32 v13, 10, v4
	v_mul_i32_i24_e32 v4, 0x400, v13
	v_sub_u32_e32 v2, v2, v4
	v_lshrrev_b32_e32 v4, 4, v2
	v_bitop3_b32 v2, v4, v2, 32 bitop3:0x6c
	v_ashrrev_i32_e32 v4, 31, v2
	v_lshrrev_b32_e32 v4, 26, v4
	v_add_u32_e32 v4, v2, v4
	v_lshlrev_b32_e32 v5, 3, v13
	v_ashrrev_i32_e32 v14, 6, v4
	v_and_b32_e32 v5, -16, v5
	v_add_u32_e32 v5, v14, v5
	v_and_b32_e32 v6, 3, v14
	s_mov_b32 s4, 0x1fffe0
	v_lshrrev_b32_e32 v7, 2, v5
	v_lshlrev_b32_e32 v8, 1, v5
	v_and_b32_e32 v4, 0xc0, v4
	v_and_or_b32 v6, v5, s4, v6
	v_and_b32_e32 v7, 4, v7
	v_and_b32_e32 v8, 24, v8
	v_sub_u32_e32 v2, v2, v4
	v_or3_b32 v6, v6, v7, v8
	v_lshlrev_b32_e32 v7, 5, v13
	v_ashrrev_i16_sdwa v2, v217, sext(v2) dst_sel:DWORD dst_unused:UNUSED_PAD src0_sel:DWORD src1_sel:BYTE_0
	v_and_b32_e32 v7, 32, v7
	v_bfe_i32 v15, v2, 0, 16
	v_add_lshl_u32 v2, v7, v15, 1
	v_lshl_add_u32 v176, v6, 11, v2
	v_lshl_add_u32 v178, v5, 11, v2
	v_bfe_i32 v2, v12, 27, 1
	v_lshrrev_b32_e32 v2, 22, v2
	v_add_u32_e32 v2, v1, v2
	v_and_b32_e32 v2, 0xfffffc00, v2
	v_sub_u32_e32 v1, v1, v2
	v_lshrrev_b32_e32 v2, 4, v1
	v_ashrrev_i32_e32 v4, 31, v12
	v_bitop3_b32 v1, v2, v1, 32 bitop3:0x6c
	v_lshrrev_b32_e32 v4, 26, v4
	v_ashrrev_i32_e32 v2, 31, v1
	v_add_u32_e32 v4, v12, v4
	v_lshrrev_b32_e32 v2, 26, v2
	v_ashrrev_i32_e32 v17, 6, v4
	v_add_u32_e32 v2, v1, v2
	v_lshlrev_b32_e32 v4, 3, v17
	v_ashrrev_i32_e32 v16, 6, v2
	v_and_b32_e32 v4, -16, v4
	v_add_u32_e32 v4, v16, v4
	v_and_b32_e32 v5, 3, v16
	v_lshrrev_b32_e32 v6, 2, v4
	v_lshlrev_b32_e32 v7, 1, v4
	v_and_b32_e32 v2, 0xc0, v2
	s_ashr_i32 s30, s28, 6
	v_and_or_b32 v5, v4, s4, v5
	v_and_b32_e32 v6, 4, v6
	v_and_b32_e32 v7, 24, v7
	v_sub_u32_e32 v1, v1, v2
	s_ashr_i32 s29, s28, 8
	s_lshl_b32 s14, s30, 10
	v_or3_b32 v5, v5, v6, v7
	v_lshlrev_b32_e32 v6, 5, v17
	v_ashrrev_i16_sdwa v1, v217, sext(v1) dst_sel:DWORD dst_unused:UNUSED_PAD src0_sel:DWORD src1_sel:BYTE_0
	v_readlane_b32 s4, v254, 18
	v_and_b32_e32 v6, 32, v6
	v_bfe_i32 v18, v1, 0, 16
	s_nop 3
	s_cmp_lt_u32 s4, 4
	s_cselect_b32 s5, 2, 0
	s_xor_b32 s4, s4, s5
	s_cmp_eq_u32 s4, 2
	s_cselect_b32 s4, 6, s4
	s_lshl_b32 s4, s4, 19
	s_mov_b32 s5, 0
	s_add_u32 s18, s0, s4
	v_add_lshl_u32 v1, v6, v18, 1
	s_addc_u32 s19, s1, s5
	s_add_i32 s15, s14, 0
	v_lshl_add_u32 v2, v5, 11, v1
	s_add_i32 m0, s15, 0x10000
	v_lshl_add_u32 v180, v4, 11, v1
	global_load_lds_dwordx4 v2, s[18:19]
	s_add_i32 m0, s15, 0x12000
	s_add_u32 s4, s18, 0x40000
	global_load_lds_dwordx4 v176, s[18:19]
	s_addc_u32 s5, s19, 0
	s_add_i32 m0, s15, 0x14000
	s_load_dwordx4 s[48:51], s[8:9], 0x70
	global_load_lds_dwordx4 v2, s[4:5]
	s_add_i32 m0, s15, 0x16000
	v_mov_b32_e32 v177, v3
	global_load_lds_dwordx4 v176, s[4:5]
	v_readlane_b32 s4, v254, 32
	v_readlane_b32 s5, v254, 33
	s_add_u32 s4, s10, s4
	s_addc_u32 s5, s11, s5
	s_add_i32 s58, s15, 0x2000
	s_mov_b32 m0, s15
	s_add_u32 s24, s4, 0x40000
	global_load_lds_dwordx4 v180, s[4:5]
	s_mov_b32 m0, s58
	s_addc_u32 s25, s5, 0
	s_add_i32 s59, s15, 0x4000
	global_load_lds_dwordx4 v178, s[4:5]
	s_mov_b32 m0, s59
	s_add_i32 s60, s15, 0x6000
	global_load_lds_dwordx4 v180, s[24:25]
	s_mov_b32 m0, s60
	v_mov_b32_e32 v181, v3
	global_load_lds_dwordx4 v178, s[24:25]
	v_mov_b32_e32 v179, v3
	s_cmp_eq_u32 s29, 1
	s_mov_b32 s72, s26
	v_lshl_add_u64 v[10:11], s[18:19], 0, v[2:3]
	v_lshl_add_u64 v[8:9], s[18:19], 0, v[176:177]
	v_lshl_add_u64 v[4:5], s[4:5], 0, v[180:181]
	s_cselect_b64 s[24:25], -1, 0
	s_cmp_lg_u32 s29, 1
	v_lshl_add_u64 v[6:7], s[4:5], 0, v[178:179]
	s_cbranch_scc1 .LBB0_87
	s_barrier
.LBB0_87:
	s_add_u32 s26, s22, 0x6b00000
	s_addc_u32 s27, s23, 0
	s_lshl_b32 s30, s30, 5
	s_and_b32 s41, s30, 0x60
	s_add_i32 m0, s15, 0x18000
	v_lshl_add_u64 v[10:11], v[10:11], 0, s[16:17]
	s_lshl_b32 s34, s72, 5
	s_lshl_b32 s40, s29, 13
	s_lshl_b32 s42, s41, 7
	s_waitcnt vmcnt(2)
	s_barrier
	global_load_lds_dwordx4 v[10:11], off
	v_lshl_add_u64 v[8:9], v[8:9], 0, s[16:17]
	s_add_i32 m0, s15, 0x1a000
	s_add_i32 s61, s15, 0x8000
	s_add_i32 s62, s15, 0xa000
	global_load_lds_dwordx4 v[8:9], off
	v_lshl_add_u64 v[4:5], v[4:5], 0, s[16:17]
	s_mov_b32 m0, s61
	s_add_u32 s30, s18, 0x40080
	global_load_lds_dwordx4 v[4:5], off
	v_lshl_add_u64 v[4:5], v[6:7], 0, s[16:17]
	s_mov_b32 m0, s62
	s_addc_u32 s31, s19, 0
	global_load_lds_dwordx4 v[4:5], off
	s_add_i32 m0, s15, 0x1c000
	v_lshl_add_u64 v[4:5], s[30:31], 0, v[2:3]
	global_load_lds_dwordx4 v[4:5], off
	v_lshl_add_u64 v[4:5], s[30:31], 0, v[176:177]
	s_add_i32 m0, s15, 0x1e000
	s_cmpk_lt_u32 s28, 0x100
	global_load_lds_dwordx4 v[4:5], off
	v_lshrrev_b32_e32 v4, 1, v12
	v_and_b32_e32 v4, 24, v4
	v_and_b32_e32 v5, 15, v12
	v_lshlrev_b32_e32 v6, 1, v4
	v_lshl_or_b32 v1, s29, 6, v5
	v_lshl_or_b32 v5, v5, 6, v6
	v_lshlrev_b32_e32 v6, 2, v12
	v_and_b32_e32 v6, 32, v6
	v_bitop3_b32 v7, v5, s40, v6 bitop3:0xde
	v_bitop3_b32 v233, v5, s42, v6 bitop3:0xde
	v_lshlrev_b32_e32 v5, 14, v17
	v_and_b32_e32 v5, 0xffff8000, v5
	v_lshl_add_u32 v5, v16, 11, v5
	v_and_b32_e32 v6, 1, v17
	v_lshl_or_b32 v5, v6, 6, v5
	v_lshl_add_u32 v182, v18, 1, v5
	v_lshlrev_b32_e32 v5, 14, v13
	v_and_b32_e32 v5, 0xffff8000, v5
	s_waitcnt vmcnt(6)
	v_lshl_add_u32 v5, v14, 11, v5
	v_and_b32_e32 v6, 1, v13
	v_or_b32_e32 v234, s41, v4
	v_lshl_or_b32 v5, v6, 6, v5
	v_readlane_b32 s40, v254, 30
	s_cselect_b64 s[28:29], -1, 0
	v_mov_b32_e32 v183, v3
	v_lshl_add_u32 v184, v15, 1, v5
	v_mov_b32_e32 v185, v3
	s_mov_b32 s63, 0
	s_mov_b32 s73, -1
	v_add_u32_e32 v235, 0, v7
	s_lshl_b64 s[30:31], s[34:35], 2
	v_lshlrev_b32_e32 v236, 2, v4
	v_readlane_b32 s34, v254, 18
	s_mov_b32 s44, s40
	s_nop 3
	s_cmp_lt_u32 s34, 4
	s_cselect_b32 s75, 2, 0
	s_xor_b32 s34, s34, s75
	s_cmp_eq_u32 s34, 2
	s_cselect_b32 s34, 6, s34
	s_barrier
	v_readlane_b32 s41, v254, 31
	s_branch .LBB0_90

.LBB0_90:
	s_add_i32 s63, s63, 1
	v_readlane_b32 s40, v252, 16
	v_readlane_b32 s42, v252, 4
	s_mul_i32 s40, s63, s40
	s_mul_hi_u32 s41, s63, s42
	s_add_i32 s41, s41, s40
	s_mul_i32 s40, s63, s42
	v_readlane_b32 s42, v252, 5
	s_add_u32 s42, s40, s42
	v_readlane_b32 s40, v252, 15
	s_addc_u32 s43, s41, s40
	v_mov_b64_e32 v[4:5], 0x240
	v_cmp_lt_i64_e64 s[40:41], s[42:43], v[4:5]
	v_mov_b64_e32 v[4:5], 0x23f
	v_cmp_gt_i64_e32 vcc, s[42:43], v[4:5]
	s_cbranch_vccnz .LBB0_92
	s_lshr_b32 s46, s42, 6
	s_mov_b32 s52, s44
	s_cmp_eq_u32 s46, 6
	s_cselect_b32 s43, 8, s46
	s_cmp_eq_u32 s46, 8
	s_cselect_b32 s46, 2, s43
.LBB0_92:
	s_ashr_i32 s53, s52, 31
	s_lshl_b64 s[42:43], s[52:53], 19
	s_add_u32 s54, s10, s42
	s_addc_u32 s55, s11, s43
	s_and_b64 s[42:43], s[40:41], exec
	s_cselect_b32 s45, s55, s5
	s_cselect_b32 s53, s54, s4
	s_ashr_i32 s47, s46, 31
	s_lshl_b64 s[42:43], s[46:47], 19
	s_add_u32 s56, s0, s42
	s_addc_u32 s57, s1, s43
	s_and_b64 s[42:43], s[40:41], exec
	s_cselect_b32 s47, s57, s19
	s_cselect_b32 s64, s56, s18
	s_add_u32 s4, s4, 0x40080
	s_addc_u32 s5, s5, 0
	s_add_u32 s65, s18, 0x100
	s_addc_u32 s66, s19, 0
	s_mov_b32 s67, -2
	s_add_u32 s18, s4, 0xfffc0080
	s_addc_u32 s19, s5, -1
	s_add_i32 s68, 0, 0x10000
	s_cmp_eq_u32 s67, 12
	s_cselect_b32 s43, s45, s19
	s_cselect_b32 s42, s53, s18
	s_cselect_b32 s19, s47, s66
	s_cselect_b32 s18, s64, s65
	s_add_i32 s70, 0, 0x14000
	v_add_u32_e32 v96, s68, v233
	v_add_u32_e32 v160, s70, v233
	ds_read_b128 v[44:47], v96
	ds_read_b128 v[64:67], v96 offset:1024
	ds_read_b128 v[76:79], v96 offset:2048
	ds_read_b128 v[96:99], v96 offset:3072
	ds_read_b128 v[116:119], v160
	ds_read_b128 v[136:139], v160 offset:1024
	ds_read_b128 v[156:159], v160 offset:2048
	ds_read_b128 v[160:163], v160 offset:3072
	v_lshl_add_u64 v[238:239], s[4:5], 0, v[182:183]
	s_add_i32 m0, s15, 0xc000
	ds_read_b128 v[164:167], v235
	ds_read_b128 v[186:189], v235 offset:1024
	ds_read_b128 v[190:193], v235 offset:2048
	ds_read_b128 v[194:197], v235 offset:3072
	ds_read_b128 v[198:201], v235 offset:4096
	ds_read_b128 v[202:205], v235 offset:5120
	ds_read_b128 v[206:209], v235 offset:6144
	ds_read_b128 v[210:213], v235 offset:7168
	global_load_lds_dwordx4 v[238:239], off
	v_lshl_add_u64 v[238:239], s[4:5], 0, v[184:185]
	s_add_i32 m0, s15, 0xe000
	s_nop 0
	global_load_lds_dwordx4 v[238:239], off
	s_waitcnt vmcnt(8)
	s_waitcnt lgkmcnt(0)
	s_barrier
	s_setprio 1
	s_waitcnt lgkmcnt(0)
	v_mfma_f32_16x16x32_bf16 v[152:155], v[44:47], v[164:167], 0
	v_mfma_f32_16x16x32_bf16 v[148:151], v[76:79], v[164:167], 0
	v_mfma_f32_16x16x32_bf16 v[132:135], v[44:47], v[190:193], 0
	v_mfma_f32_16x16x32_bf16 v[128:131], v[76:79], v[190:193], 0
	v_mfma_f32_16x16x32_bf16 v[112:115], v[44:47], v[198:201], 0
	v_mfma_f32_16x16x32_bf16 v[108:111], v[76:79], v[198:201], 0
	v_mfma_f32_16x16x32_bf16 v[92:95], v[44:47], v[206:209], 0
	v_mfma_f32_16x16x32_bf16 v[88:91], v[76:79], v[206:209], 0
	v_mfma_f32_16x16x32_bf16 v[152:155], v[64:67], v[186:189], v[152:155]
	v_mfma_f32_16x16x32_bf16 v[148:151], v[96:99], v[186:189], v[148:151]
	v_mfma_f32_16x16x32_bf16 v[132:135], v[64:67], v[194:197], v[132:135]
	v_mfma_f32_16x16x32_bf16 v[128:131], v[96:99], v[194:197], v[128:131]
	v_mfma_f32_16x16x32_bf16 v[112:115], v[64:67], v[202:205], v[112:115]
	v_mfma_f32_16x16x32_bf16 v[108:111], v[96:99], v[202:205], v[108:111]
	v_mfma_f32_16x16x32_bf16 v[92:95], v[64:67], v[210:213], v[92:95]
	v_mfma_f32_16x16x32_bf16 v[88:91], v[96:99], v[210:213], v[88:91]
	s_setprio 0
	s_setprio 1
	v_mfma_f32_16x16x32_bf16 v[144:147], v[116:119], v[164:167], 0
	v_mfma_f32_16x16x32_bf16 v[140:143], v[156:159], v[164:167], 0
	v_mfma_f32_16x16x32_bf16 v[124:127], v[116:119], v[190:193], 0
	v_mfma_f32_16x16x32_bf16 v[120:123], v[156:159], v[190:193], 0
	v_mfma_f32_16x16x32_bf16 v[104:107], v[116:119], v[198:201], 0
	v_mfma_f32_16x16x32_bf16 v[100:103], v[156:159], v[198:201], 0
	v_mfma_f32_16x16x32_bf16 v[84:87], v[116:119], v[206:209], 0
	v_mfma_f32_16x16x32_bf16 v[80:83], v[156:159], v[206:209], 0
	v_mfma_f32_16x16x32_bf16 v[144:147], v[136:139], v[186:189], v[144:147]
	v_mfma_f32_16x16x32_bf16 v[140:143], v[160:163], v[186:189], v[140:143]
	v_mfma_f32_16x16x32_bf16 v[124:127], v[136:139], v[194:197], v[124:127]
	v_mfma_f32_16x16x32_bf16 v[120:123], v[160:163], v[194:197], v[120:123]
	v_mfma_f32_16x16x32_bf16 v[104:107], v[136:139], v[202:205], v[104:107]
	v_mfma_f32_16x16x32_bf16 v[100:103], v[160:163], v[202:205], v[100:103]
	v_mfma_f32_16x16x32_bf16 v[84:87], v[136:139], v[210:213], v[84:87]
	v_mfma_f32_16x16x32_bf16 v[80:83], v[160:163], v[210:213], v[80:83]
	s_setprio 0
	s_barrier
	s_add_i32 s68, s68, s14
	v_lshl_add_u64 v[238:239], s[18:19], 0, v[2:3]
	s_mov_b32 m0, s68
	ds_read_b128 v[164:167], v235 offset:16384
	ds_read_b128 v[186:189], v235 offset:17408
	ds_read_b128 v[190:193], v235 offset:18432
	ds_read_b128 v[194:197], v235 offset:19456
	ds_read_b128 v[198:201], v235 offset:20480
	ds_read_b128 v[202:205], v235 offset:21504
	ds_read_b128 v[206:209], v235 offset:22528
	ds_read_b128 v[210:213], v235 offset:23552
	global_load_lds_dwordx4 v[238:239], off
	s_add_i32 m0, s68, 0x2000
	s_add_u32 s68, s18, 0x40000
	v_lshl_add_u64 v[240:241], s[18:19], 0, v[176:177]
	s_addc_u32 s69, s19, 0
	s_add_i32 s70, s70, s14
	global_load_lds_dwordx4 v[240:241], off
	v_lshl_add_u64 v[242:243], s[68:69], 0, v[2:3]
	s_mov_b32 m0, s70
	v_lshl_add_u64 v[244:245], s[42:43], 0, v[178:179]
	global_load_lds_dwordx4 v[242:243], off
	v_lshl_add_u64 v[242:243], s[68:69], 0, v[176:177]
	s_add_i32 m0, s70, 0x2000
	s_nop 0
	global_load_lds_dwordx4 v[242:243], off
	v_lshl_add_u64 v[242:243], s[42:43], 0, v[180:181]
	s_mov_b32 m0, s15
	s_nop 0
	global_load_lds_dwordx4 v[242:243], off
	s_mov_b32 m0, s58
	s_nop 0
	global_load_lds_dwordx4 v[244:245], off
	s_waitcnt vmcnt(8)
	s_waitcnt lgkmcnt(0)
	s_barrier
	s_setprio 1
	s_waitcnt lgkmcnt(0)
	v_mfma_f32_16x16x32_bf16 v[72:75], v[44:47], v[164:167], 0
	v_mfma_f32_16x16x32_bf16 v[68:71], v[76:79], v[164:167], 0
	v_mfma_f32_16x16x32_bf16 v[52:55], v[44:47], v[190:193], 0
	v_mfma_f32_16x16x32_bf16 v[48:51], v[76:79], v[190:193], 0
	v_mfma_f32_16x16x32_bf16 v[32:35], v[44:47], v[198:201], 0
	v_mfma_f32_16x16x32_bf16 v[28:31], v[76:79], v[198:201], 0
	v_mfma_f32_16x16x32_bf16 v[16:19], v[44:47], v[206:209], 0
	v_mfma_f32_16x16x32_bf16 v[12:15], v[76:79], v[206:209], 0
	v_mfma_f32_16x16x32_bf16 v[72:75], v[64:67], v[186:189], v[72:75]
	v_mfma_f32_16x16x32_bf16 v[68:71], v[96:99], v[186:189], v[68:71]
	v_mfma_f32_16x16x32_bf16 v[52:55], v[64:67], v[194:197], v[52:55]
	v_mfma_f32_16x16x32_bf16 v[48:51], v[96:99], v[194:197], v[48:51]
	v_mfma_f32_16x16x32_bf16 v[32:35], v[64:67], v[202:205], v[32:35]
	v_mfma_f32_16x16x32_bf16 v[28:31], v[96:99], v[202:205], v[28:31]
	v_mfma_f32_16x16x32_bf16 v[16:19], v[64:67], v[210:213], v[16:19]
	v_mfma_f32_16x16x32_bf16 v[12:15], v[96:99], v[210:213], v[12:15]
	s_setprio 0
	s_setprio 1
	v_mfma_f32_16x16x32_bf16 v[56:59], v[156:159], v[164:167], 0
	v_mfma_f32_16x16x32_bf16 v[40:43], v[116:119], v[190:193], 0
	v_mfma_f32_16x16x32_bf16 v[36:39], v[156:159], v[190:193], 0
	v_mfma_f32_16x16x32_bf16 v[24:27], v[116:119], v[198:201], 0
	v_mfma_f32_16x16x32_bf16 v[20:23], v[156:159], v[198:201], 0
	v_mfma_f32_16x16x32_bf16 v[8:11], v[116:119], v[206:209], 0
	v_mfma_f32_16x16x32_bf16 v[4:7], v[156:159], v[206:209], 0
	v_mfma_f32_16x16x32_bf16 v[44:47], v[116:119], v[164:167], 0
	v_mfma_f32_16x16x32_bf16 v[56:59], v[160:163], v[186:189], v[56:59]
	v_mfma_f32_16x16x32_bf16 v[40:43], v[136:139], v[194:197], v[40:43]
	v_mfma_f32_16x16x32_bf16 v[36:39], v[160:163], v[194:197], v[36:39]
	v_mfma_f32_16x16x32_bf16 v[24:27], v[136:139], v[202:205], v[24:27]
	v_mfma_f32_16x16x32_bf16 v[20:23], v[160:163], v[202:205], v[20:23]
	v_mfma_f32_16x16x32_bf16 v[8:11], v[136:139], v[210:213], v[8:11]
	v_mfma_f32_16x16x32_bf16 v[4:7], v[160:163], v[210:213], v[4:7]
	v_mfma_f32_16x16x32_bf16 v[44:47], v[136:139], v[186:189], v[44:47]
	s_setprio 0
	s_barrier
	s_add_i32 s68, 0, 0x18000
	s_add_i32 s69, 0, 0x1c000
	v_add_u32_e32 v96, s68, v233
	v_add_u32_e32 v160, s69, v233
	ds_read_b128 v[60:63], v96
	ds_read_b128 v[64:67], v96 offset:1024
	ds_read_b128 v[76:79], v96 offset:2048
	ds_read_b128 v[96:99], v96 offset:3072
	ds_read_b128 v[116:119], v160
	ds_read_b128 v[136:139], v160 offset:1024
	ds_read_b128 v[156:159], v160 offset:2048
	ds_read_b128 v[160:163], v160 offset:3072
	s_add_u32 s42, s42, 0x40000
	s_addc_u32 s43, s43, 0
	s_mov_b32 m0, s59
	v_lshl_add_u64 v[246:247], s[42:43], 0, v[180:181]
	ds_read_b128 v[164:167], v235 offset:32768
	ds_read_b128 v[186:189], v235 offset:33792
	ds_read_b128 v[190:193], v235 offset:34816
	ds_read_b128 v[194:197], v235 offset:35840
	ds_read_b128 v[198:201], v235 offset:36864
	ds_read_b128 v[202:205], v235 offset:37888
	ds_read_b128 v[206:209], v235 offset:38912
	ds_read_b128 v[210:213], v235 offset:39936
	global_load_lds_dwordx4 v[246:247], off
	v_lshl_add_u64 v[246:247], s[42:43], 0, v[178:179]
	s_mov_b32 m0, s60
	s_nop 0
	global_load_lds_dwordx4 v[246:247], off
	s_waitcnt vmcnt(8)
	s_waitcnt lgkmcnt(0)
	s_barrier
	s_setprio 1
	s_waitcnt lgkmcnt(0)
	v_mfma_f32_16x16x32_bf16 v[152:155], v[60:63], v[164:167], v[152:155]
	v_mfma_f32_16x16x32_bf16 v[148:151], v[76:79], v[164:167], v[148:151]
	v_mfma_f32_16x16x32_bf16 v[132:135], v[60:63], v[190:193], v[132:135]
	v_mfma_f32_16x16x32_bf16 v[128:131], v[76:79], v[190:193], v[128:131]
	v_mfma_f32_16x16x32_bf16 v[112:115], v[60:63], v[198:201], v[112:115]
	v_mfma_f32_16x16x32_bf16 v[108:111], v[76:79], v[198:201], v[108:111]
	v_mfma_f32_16x16x32_bf16 v[92:95], v[60:63], v[206:209], v[92:95]
	v_mfma_f32_16x16x32_bf16 v[88:91], v[76:79], v[206:209], v[88:91]
	v_mfma_f32_16x16x32_bf16 v[152:155], v[64:67], v[186:189], v[152:155]
	v_mfma_f32_16x16x32_bf16 v[148:151], v[96:99], v[186:189], v[148:151]
	v_mfma_f32_16x16x32_bf16 v[132:135], v[64:67], v[194:197], v[132:135]
	v_mfma_f32_16x16x32_bf16 v[128:131], v[96:99], v[194:197], v[128:131]
	v_mfma_f32_16x16x32_bf16 v[112:115], v[64:67], v[202:205], v[112:115]
	v_mfma_f32_16x16x32_bf16 v[108:111], v[96:99], v[202:205], v[108:111]
	v_mfma_f32_16x16x32_bf16 v[92:95], v[64:67], v[210:213], v[92:95]
	v_mfma_f32_16x16x32_bf16 v[88:91], v[96:99], v[210:213], v[88:91]
	s_setprio 0
	s_setprio 1
	v_mfma_f32_16x16x32_bf16 v[144:147], v[116:119], v[164:167], v[144:147]
	v_mfma_f32_16x16x32_bf16 v[140:143], v[156:159], v[164:167], v[140:143]
	v_mfma_f32_16x16x32_bf16 v[124:127], v[116:119], v[190:193], v[124:127]
	v_mfma_f32_16x16x32_bf16 v[120:123], v[156:159], v[190:193], v[120:123]
	v_mfma_f32_16x16x32_bf16 v[104:107], v[116:119], v[198:201], v[104:107]
	v_mfma_f32_16x16x32_bf16 v[100:103], v[156:159], v[198:201], v[100:103]
	v_mfma_f32_16x16x32_bf16 v[84:87], v[116:119], v[206:209], v[84:87]
	v_mfma_f32_16x16x32_bf16 v[80:83], v[156:159], v[206:209], v[80:83]
	v_mfma_f32_16x16x32_bf16 v[144:147], v[136:139], v[186:189], v[144:147]
	v_mfma_f32_16x16x32_bf16 v[140:143], v[160:163], v[186:189], v[140:143]
	v_mfma_f32_16x16x32_bf16 v[124:127], v[136:139], v[194:197], v[124:127]
	v_mfma_f32_16x16x32_bf16 v[120:123], v[160:163], v[194:197], v[120:123]
	v_mfma_f32_16x16x32_bf16 v[104:107], v[136:139], v[202:205], v[104:107]
	v_mfma_f32_16x16x32_bf16 v[100:103], v[160:163], v[202:205], v[100:103]
	v_mfma_f32_16x16x32_bf16 v[84:87], v[136:139], v[210:213], v[84:87]
	v_mfma_f32_16x16x32_bf16 v[80:83], v[160:163], v[210:213], v[80:83]
	s_setprio 0
	s_barrier
	s_add_i32 s42, s68, s14
	v_lshl_add_u64 v[238:239], v[238:239], 0, s[16:17]
	s_mov_b32 m0, s42
	ds_read_b128 v[164:167], v235 offset:49152
	ds_read_b128 v[186:189], v235 offset:50176
	ds_read_b128 v[190:193], v235 offset:51200
	ds_read_b128 v[194:197], v235 offset:52224
	ds_read_b128 v[198:201], v235 offset:53248
	ds_read_b128 v[202:205], v235 offset:54272
	ds_read_b128 v[206:209], v235 offset:55296
	ds_read_b128 v[210:213], v235 offset:56320
	global_load_lds_dwordx4 v[238:239], off
	s_add_i32 m0, s42, 0x2000
	s_add_u32 s18, s18, 0x40080
	v_lshl_add_u64 v[238:239], v[240:241], 0, s[16:17]
	s_addc_u32 s19, s19, 0
	s_add_i32 s42, s69, s14
	global_load_lds_dwordx4 v[238:239], off
	v_lshl_add_u64 v[238:239], s[18:19], 0, v[2:3]
	s_mov_b32 m0, s42
	s_nop 0
	global_load_lds_dwordx4 v[238:239], off
	v_lshl_add_u64 v[238:239], s[18:19], 0, v[176:177]
	s_add_i32 m0, s42, 0x2000
	s_nop 0
	global_load_lds_dwordx4 v[238:239], off
	v_lshl_add_u64 v[238:239], v[242:243], 0, s[16:17]
	s_mov_b32 m0, s61
	s_nop 0
	global_load_lds_dwordx4 v[238:239], off
	v_lshl_add_u64 v[238:239], v[244:245], 0, s[16:17]
	s_mov_b32 m0, s62
	s_nop 0
	global_load_lds_dwordx4 v[238:239], off
	s_waitcnt vmcnt(8)
	s_waitcnt lgkmcnt(0)
	s_barrier
	s_setprio 1
	s_waitcnt lgkmcnt(0)
	v_mfma_f32_16x16x32_bf16 v[72:75], v[60:63], v[164:167], v[72:75]
	v_mfma_f32_16x16x32_bf16 v[68:71], v[76:79], v[164:167], v[68:71]
	v_mfma_f32_16x16x32_bf16 v[52:55], v[60:63], v[190:193], v[52:55]
	v_mfma_f32_16x16x32_bf16 v[48:51], v[76:79], v[190:193], v[48:51]
	v_mfma_f32_16x16x32_bf16 v[32:35], v[60:63], v[198:201], v[32:35]
	v_mfma_f32_16x16x32_bf16 v[28:31], v[76:79], v[198:201], v[28:31]
	v_mfma_f32_16x16x32_bf16 v[16:19], v[60:63], v[206:209], v[16:19]
	v_mfma_f32_16x16x32_bf16 v[12:15], v[76:79], v[206:209], v[12:15]
	v_mfma_f32_16x16x32_bf16 v[72:75], v[64:67], v[186:189], v[72:75]
	v_mfma_f32_16x16x32_bf16 v[68:71], v[96:99], v[186:189], v[68:71]
	v_mfma_f32_16x16x32_bf16 v[52:55], v[64:67], v[194:197], v[52:55]
	v_mfma_f32_16x16x32_bf16 v[48:51], v[96:99], v[194:197], v[48:51]
	v_mfma_f32_16x16x32_bf16 v[32:35], v[64:67], v[202:205], v[32:35]
	v_mfma_f32_16x16x32_bf16 v[28:31], v[96:99], v[202:205], v[28:31]
	v_mfma_f32_16x16x32_bf16 v[16:19], v[64:67], v[210:213], v[16:19]
	v_mfma_f32_16x16x32_bf16 v[12:15], v[96:99], v[210:213], v[12:15]
	s_setprio 0
	s_setprio 1
	v_mfma_f32_16x16x32_bf16 v[44:47], v[116:119], v[164:167], v[44:47]
	v_mfma_f32_16x16x32_bf16 v[60:63], v[136:139], v[186:189], v[44:47]
	v_mfma_f32_16x16x32_bf16 v[44:47], v[156:159], v[164:167], v[56:59]
	v_mfma_f32_16x16x32_bf16 v[40:43], v[116:119], v[190:193], v[40:43]
	v_mfma_f32_16x16x32_bf16 v[36:39], v[156:159], v[190:193], v[36:39]
	v_mfma_f32_16x16x32_bf16 v[24:27], v[116:119], v[198:201], v[24:27]
	v_mfma_f32_16x16x32_bf16 v[20:23], v[156:159], v[198:201], v[20:23]
	v_mfma_f32_16x16x32_bf16 v[8:11], v[116:119], v[206:209], v[8:11]
	v_mfma_f32_16x16x32_bf16 v[4:7], v[156:159], v[206:209], v[4:7]
	v_mfma_f32_16x16x32_bf16 v[56:59], v[160:163], v[186:189], v[44:47]
	v_mfma_f32_16x16x32_bf16 v[40:43], v[136:139], v[194:197], v[40:43]
	v_mfma_f32_16x16x32_bf16 v[36:39], v[160:163], v[194:197], v[36:39]
	v_mfma_f32_16x16x32_bf16 v[24:27], v[136:139], v[202:205], v[24:27]
	v_mfma_f32_16x16x32_bf16 v[20:23], v[160:163], v[202:205], v[20:23]
	v_mfma_f32_16x16x32_bf16 v[8:11], v[136:139], v[210:213], v[8:11]
	v_mfma_f32_16x16x32_bf16 v[4:7], v[160:163], v[210:213], v[4:7]
	s_setprio 0
	s_barrier
	s_add_i32 s67, s67, 2
	s_add_u32 s4, s4, 0x100
	s_addc_u32 s5, s5, 0
	s_add_u32 s65, s65, 0x100
	s_addc_u32 s66, s66, 0
	s_cmp_gt_u32 s67, 13
	s_cmp_eq_u32 s63, 3
	s_cbranch_scc0 .Lea_in_skip
	v_readlane_b32 s84, v255, 62
	s_nop 3
	s_cmp_eq_u32 s84, 0
	s_cbranch_scc1 .Lea_in_skip
	s_mov_b64 s[86:87], exec
	v_readlane_b32 s88, v252, 11
	v_readlane_b32 s89, v252, 12
	s_nop 3
	s_and_b64 s[88:89], s[86:87], s[88:89]
	s_mov_b64 exec, s[88:89]
	s_cbranch_execz .Lea_in_rest
	v_readlane_b32 s90, v253, 26
	v_readlane_b32 s91, v253, 27
	s_nop 3
	s_add_u32 s90, s90, 0x2300
	s_addc_u32 s91, s91, 0
	v_mov_b32_e32 v248, 0
	v_mov_b32_e32 v249, 1
	s_nop 1
	global_atomic_add v248, v249, s[90:91]
.Lea_in_rest:
	s_mov_b64 exec, s[86:87]
.Lea_in_skip:
.LBB0_93:
	s_add_u32 s18, s4, 0xfffc0080
	s_addc_u32 s19, s5, -1
	s_add_i32 s68, 0, 0x10000
	s_cmp_eq_u32 s67, 12
	s_cselect_b32 s43, s45, s19
	s_cselect_b32 s42, s53, s18
	s_cselect_b32 s19, s47, s66
	s_cselect_b32 s18, s64, s65
	s_add_i32 s70, 0, 0x14000
	v_add_u32_e32 v96, s68, v233
	v_add_u32_e32 v160, s70, v233
	ds_read_b128 v[44:47], v96
	ds_read_b128 v[64:67], v96 offset:1024
	ds_read_b128 v[76:79], v96 offset:2048
	ds_read_b128 v[96:99], v96 offset:3072
	ds_read_b128 v[116:119], v160
	ds_read_b128 v[136:139], v160 offset:1024
	ds_read_b128 v[156:159], v160 offset:2048
	ds_read_b128 v[160:163], v160 offset:3072
	v_lshl_add_u64 v[238:239], s[4:5], 0, v[182:183]
	s_add_i32 m0, s15, 0xc000
	ds_read_b128 v[164:167], v235
	ds_read_b128 v[186:189], v235 offset:1024
	ds_read_b128 v[190:193], v235 offset:2048
	ds_read_b128 v[194:197], v235 offset:3072
	ds_read_b128 v[198:201], v235 offset:4096
	ds_read_b128 v[202:205], v235 offset:5120
	ds_read_b128 v[206:209], v235 offset:6144
	ds_read_b128 v[210:213], v235 offset:7168
	global_load_lds_dwordx4 v[238:239], off
	v_lshl_add_u64 v[238:239], s[4:5], 0, v[184:185]
	s_add_i32 m0, s15, 0xe000
	s_nop 0
	global_load_lds_dwordx4 v[238:239], off
	s_waitcnt vmcnt(8)
	s_waitcnt lgkmcnt(0)
	s_barrier
	s_setprio 1
	s_waitcnt lgkmcnt(0)
	v_mfma_f32_16x16x32_bf16 v[152:155], v[44:47], v[164:167], v[152:155]
	v_mfma_f32_16x16x32_bf16 v[148:151], v[76:79], v[164:167], v[148:151]
	v_mfma_f32_16x16x32_bf16 v[132:135], v[44:47], v[190:193], v[132:135]
	v_mfma_f32_16x16x32_bf16 v[128:131], v[76:79], v[190:193], v[128:131]
	v_mfma_f32_16x16x32_bf16 v[112:115], v[44:47], v[198:201], v[112:115]
	v_mfma_f32_16x16x32_bf16 v[108:111], v[76:79], v[198:201], v[108:111]
	v_mfma_f32_16x16x32_bf16 v[92:95], v[44:47], v[206:209], v[92:95]
	v_mfma_f32_16x16x32_bf16 v[88:91], v[76:79], v[206:209], v[88:91]
	v_mfma_f32_16x16x32_bf16 v[152:155], v[64:67], v[186:189], v[152:155]
	v_mfma_f32_16x16x32_bf16 v[148:151], v[96:99], v[186:189], v[148:151]
	v_mfma_f32_16x16x32_bf16 v[132:135], v[64:67], v[194:197], v[132:135]
	v_mfma_f32_16x16x32_bf16 v[128:131], v[96:99], v[194:197], v[128:131]
	v_mfma_f32_16x16x32_bf16 v[112:115], v[64:67], v[202:205], v[112:115]
	v_mfma_f32_16x16x32_bf16 v[108:111], v[96:99], v[202:205], v[108:111]
	v_mfma_f32_16x16x32_bf16 v[92:95], v[64:67], v[210:213], v[92:95]
	v_mfma_f32_16x16x32_bf16 v[88:91], v[96:99], v[210:213], v[88:91]
	s_setprio 0
	s_setprio 1
	v_mfma_f32_16x16x32_bf16 v[144:147], v[116:119], v[164:167], v[144:147]
	v_mfma_f32_16x16x32_bf16 v[140:143], v[156:159], v[164:167], v[140:143]
	v_mfma_f32_16x16x32_bf16 v[124:127], v[116:119], v[190:193], v[124:127]
	v_mfma_f32_16x16x32_bf16 v[120:123], v[156:159], v[190:193], v[120:123]
	v_mfma_f32_16x16x32_bf16 v[104:107], v[116:119], v[198:201], v[104:107]
	v_mfma_f32_16x16x32_bf16 v[100:103], v[156:159], v[198:201], v[100:103]
	v_mfma_f32_16x16x32_bf16 v[84:87], v[116:119], v[206:209], v[84:87]
	v_mfma_f32_16x16x32_bf16 v[80:83], v[156:159], v[206:209], v[80:83]
	v_mfma_f32_16x16x32_bf16 v[144:147], v[136:139], v[186:189], v[144:147]
	v_mfma_f32_16x16x32_bf16 v[140:143], v[160:163], v[186:189], v[140:143]
	v_mfma_f32_16x16x32_bf16 v[124:127], v[136:139], v[194:197], v[124:127]
	v_mfma_f32_16x16x32_bf16 v[120:123], v[160:163], v[194:197], v[120:123]
	v_mfma_f32_16x16x32_bf16 v[104:107], v[136:139], v[202:205], v[104:107]
	v_mfma_f32_16x16x32_bf16 v[100:103], v[160:163], v[202:205], v[100:103]
	v_mfma_f32_16x16x32_bf16 v[84:87], v[136:139], v[210:213], v[84:87]
	v_mfma_f32_16x16x32_bf16 v[80:83], v[160:163], v[210:213], v[80:83]
	s_setprio 0
	s_barrier
	s_add_i32 s68, s68, s14
	v_lshl_add_u64 v[238:239], s[18:19], 0, v[2:3]
	s_mov_b32 m0, s68
	ds_read_b128 v[164:167], v235 offset:16384
	ds_read_b128 v[186:189], v235 offset:17408
	ds_read_b128 v[190:193], v235 offset:18432
	ds_read_b128 v[194:197], v235 offset:19456
	ds_read_b128 v[198:201], v235 offset:20480
	ds_read_b128 v[202:205], v235 offset:21504
	ds_read_b128 v[206:209], v235 offset:22528
	ds_read_b128 v[210:213], v235 offset:23552
	global_load_lds_dwordx4 v[238:239], off
	s_add_i32 m0, s68, 0x2000
	s_add_u32 s68, s18, 0x40000
	v_lshl_add_u64 v[240:241], s[18:19], 0, v[176:177]
	s_addc_u32 s69, s19, 0
	s_add_i32 s70, s70, s14
	global_load_lds_dwordx4 v[240:241], off
	v_lshl_add_u64 v[242:243], s[68:69], 0, v[2:3]
	s_mov_b32 m0, s70
	v_lshl_add_u64 v[244:245], s[42:43], 0, v[178:179]
	global_load_lds_dwordx4 v[242:243], off
	v_lshl_add_u64 v[242:243], s[68:69], 0, v[176:177]
	s_add_i32 m0, s70, 0x2000
	s_nop 0
	global_load_lds_dwordx4 v[242:243], off
	v_lshl_add_u64 v[242:243], s[42:43], 0, v[180:181]
	s_mov_b32 m0, s15
	s_nop 0
	global_load_lds_dwordx4 v[242:243], off
	s_mov_b32 m0, s58
	s_nop 0
	global_load_lds_dwordx4 v[244:245], off
	s_waitcnt vmcnt(8)
	s_waitcnt lgkmcnt(0)
	s_barrier
	s_setprio 1
	s_waitcnt lgkmcnt(0)
	v_mfma_f32_16x16x32_bf16 v[72:75], v[44:47], v[164:167], v[72:75]
	v_mfma_f32_16x16x32_bf16 v[68:71], v[76:79], v[164:167], v[68:71]
	v_mfma_f32_16x16x32_bf16 v[52:55], v[44:47], v[190:193], v[52:55]
	v_mfma_f32_16x16x32_bf16 v[48:51], v[76:79], v[190:193], v[48:51]
	v_mfma_f32_16x16x32_bf16 v[32:35], v[44:47], v[198:201], v[32:35]
	v_mfma_f32_16x16x32_bf16 v[28:31], v[76:79], v[198:201], v[28:31]
	v_mfma_f32_16x16x32_bf16 v[16:19], v[44:47], v[206:209], v[16:19]
	v_mfma_f32_16x16x32_bf16 v[12:15], v[76:79], v[206:209], v[12:15]
	v_mfma_f32_16x16x32_bf16 v[72:75], v[64:67], v[186:189], v[72:75]
	v_mfma_f32_16x16x32_bf16 v[68:71], v[96:99], v[186:189], v[68:71]
	v_mfma_f32_16x16x32_bf16 v[52:55], v[64:67], v[194:197], v[52:55]
	v_mfma_f32_16x16x32_bf16 v[48:51], v[96:99], v[194:197], v[48:51]
	v_mfma_f32_16x16x32_bf16 v[32:35], v[64:67], v[202:205], v[32:35]
	v_mfma_f32_16x16x32_bf16 v[28:31], v[96:99], v[202:205], v[28:31]
	v_mfma_f32_16x16x32_bf16 v[16:19], v[64:67], v[210:213], v[16:19]
	v_mfma_f32_16x16x32_bf16 v[12:15], v[96:99], v[210:213], v[12:15]
	s_setprio 0
	s_setprio 1
	v_mfma_f32_16x16x32_bf16 v[56:59], v[156:159], v[164:167], v[56:59]
	v_mfma_f32_16x16x32_bf16 v[40:43], v[116:119], v[190:193], v[40:43]
	v_mfma_f32_16x16x32_bf16 v[36:39], v[156:159], v[190:193], v[36:39]
	v_mfma_f32_16x16x32_bf16 v[24:27], v[116:119], v[198:201], v[24:27]
	v_mfma_f32_16x16x32_bf16 v[20:23], v[156:159], v[198:201], v[20:23]
	v_mfma_f32_16x16x32_bf16 v[8:11], v[116:119], v[206:209], v[8:11]
	v_mfma_f32_16x16x32_bf16 v[4:7], v[156:159], v[206:209], v[4:7]
	v_mfma_f32_16x16x32_bf16 v[44:47], v[116:119], v[164:167], v[60:63]
	v_mfma_f32_16x16x32_bf16 v[56:59], v[160:163], v[186:189], v[56:59]
	v_mfma_f32_16x16x32_bf16 v[40:43], v[136:139], v[194:197], v[40:43]
	v_mfma_f32_16x16x32_bf16 v[36:39], v[160:163], v[194:197], v[36:39]
	v_mfma_f32_16x16x32_bf16 v[24:27], v[136:139], v[202:205], v[24:27]
	v_mfma_f32_16x16x32_bf16 v[20:23], v[160:163], v[202:205], v[20:23]
	v_mfma_f32_16x16x32_bf16 v[8:11], v[136:139], v[210:213], v[8:11]
	v_mfma_f32_16x16x32_bf16 v[4:7], v[160:163], v[210:213], v[4:7]
	v_mfma_f32_16x16x32_bf16 v[44:47], v[136:139], v[186:189], v[44:47]
	s_setprio 0
	s_barrier
	s_add_i32 s68, 0, 0x18000
	s_add_i32 s69, 0, 0x1c000
	v_add_u32_e32 v96, s68, v233
	v_add_u32_e32 v160, s69, v233
	ds_read_b128 v[60:63], v96
	ds_read_b128 v[64:67], v96 offset:1024
	ds_read_b128 v[76:79], v96 offset:2048
	ds_read_b128 v[96:99], v96 offset:3072
	ds_read_b128 v[116:119], v160
	ds_read_b128 v[136:139], v160 offset:1024
	ds_read_b128 v[156:159], v160 offset:2048
	ds_read_b128 v[160:163], v160 offset:3072
	s_add_u32 s42, s42, 0x40000
	s_addc_u32 s43, s43, 0
	s_mov_b32 m0, s59
	v_lshl_add_u64 v[246:247], s[42:43], 0, v[180:181]
	ds_read_b128 v[164:167], v235 offset:32768
	ds_read_b128 v[186:189], v235 offset:33792
	ds_read_b128 v[190:193], v235 offset:34816
	ds_read_b128 v[194:197], v235 offset:35840
	ds_read_b128 v[198:201], v235 offset:36864
	ds_read_b128 v[202:205], v235 offset:37888
	ds_read_b128 v[206:209], v235 offset:38912
	ds_read_b128 v[210:213], v235 offset:39936
	global_load_lds_dwordx4 v[246:247], off
	v_lshl_add_u64 v[246:247], s[42:43], 0, v[178:179]
	s_mov_b32 m0, s60
	s_nop 0
	global_load_lds_dwordx4 v[246:247], off
	s_waitcnt vmcnt(8)
	s_waitcnt lgkmcnt(0)
	s_barrier
	s_setprio 1
	s_waitcnt lgkmcnt(0)
	v_mfma_f32_16x16x32_bf16 v[152:155], v[60:63], v[164:167], v[152:155]
	v_mfma_f32_16x16x32_bf16 v[148:151], v[76:79], v[164:167], v[148:151]
	v_mfma_f32_16x16x32_bf16 v[132:135], v[60:63], v[190:193], v[132:135]
	v_mfma_f32_16x16x32_bf16 v[128:131], v[76:79], v[190:193], v[128:131]
	v_mfma_f32_16x16x32_bf16 v[112:115], v[60:63], v[198:201], v[112:115]
	v_mfma_f32_16x16x32_bf16 v[108:111], v[76:79], v[198:201], v[108:111]
	v_mfma_f32_16x16x32_bf16 v[92:95], v[60:63], v[206:209], v[92:95]
	v_mfma_f32_16x16x32_bf16 v[88:91], v[76:79], v[206:209], v[88:91]
	v_mfma_f32_16x16x32_bf16 v[152:155], v[64:67], v[186:189], v[152:155]
	v_mfma_f32_16x16x32_bf16 v[148:151], v[96:99], v[186:189], v[148:151]
	v_mfma_f32_16x16x32_bf16 v[132:135], v[64:67], v[194:197], v[132:135]
	v_mfma_f32_16x16x32_bf16 v[128:131], v[96:99], v[194:197], v[128:131]
	v_mfma_f32_16x16x32_bf16 v[112:115], v[64:67], v[202:205], v[112:115]
	v_mfma_f32_16x16x32_bf16 v[108:111], v[96:99], v[202:205], v[108:111]
	v_mfma_f32_16x16x32_bf16 v[92:95], v[64:67], v[210:213], v[92:95]
	v_mfma_f32_16x16x32_bf16 v[88:91], v[96:99], v[210:213], v[88:91]
	s_setprio 0
	s_setprio 1
	v_mfma_f32_16x16x32_bf16 v[144:147], v[116:119], v[164:167], v[144:147]
	v_mfma_f32_16x16x32_bf16 v[140:143], v[156:159], v[164:167], v[140:143]
	v_mfma_f32_16x16x32_bf16 v[124:127], v[116:119], v[190:193], v[124:127]
	v_mfma_f32_16x16x32_bf16 v[120:123], v[156:159], v[190:193], v[120:123]
	v_mfma_f32_16x16x32_bf16 v[104:107], v[116:119], v[198:201], v[104:107]
	v_mfma_f32_16x16x32_bf16 v[100:103], v[156:159], v[198:201], v[100:103]
	v_mfma_f32_16x16x32_bf16 v[84:87], v[116:119], v[206:209], v[84:87]
	v_mfma_f32_16x16x32_bf16 v[80:83], v[156:159], v[206:209], v[80:83]
	v_mfma_f32_16x16x32_bf16 v[144:147], v[136:139], v[186:189], v[144:147]
	v_mfma_f32_16x16x32_bf16 v[140:143], v[160:163], v[186:189], v[140:143]
	v_mfma_f32_16x16x32_bf16 v[124:127], v[136:139], v[194:197], v[124:127]
	v_mfma_f32_16x16x32_bf16 v[120:123], v[160:163], v[194:197], v[120:123]
	v_mfma_f32_16x16x32_bf16 v[104:107], v[136:139], v[202:205], v[104:107]
	v_mfma_f32_16x16x32_bf16 v[100:103], v[160:163], v[202:205], v[100:103]
	v_mfma_f32_16x16x32_bf16 v[84:87], v[136:139], v[210:213], v[84:87]
	v_mfma_f32_16x16x32_bf16 v[80:83], v[160:163], v[210:213], v[80:83]
	s_setprio 0
	s_barrier
	s_add_i32 s42, s68, s14
	v_lshl_add_u64 v[238:239], v[238:239], 0, s[16:17]
	s_mov_b32 m0, s42
	ds_read_b128 v[164:167], v235 offset:49152
	ds_read_b128 v[186:189], v235 offset:50176
	ds_read_b128 v[190:193], v235 offset:51200
	ds_read_b128 v[194:197], v235 offset:52224
	ds_read_b128 v[198:201], v235 offset:53248
	ds_read_b128 v[202:205], v235 offset:54272
	ds_read_b128 v[206:209], v235 offset:55296
	ds_read_b128 v[210:213], v235 offset:56320
	global_load_lds_dwordx4 v[238:239], off
	s_add_i32 m0, s42, 0x2000
	s_add_u32 s18, s18, 0x40080
	v_lshl_add_u64 v[238:239], v[240:241], 0, s[16:17]
	s_addc_u32 s19, s19, 0
	s_add_i32 s42, s69, s14
	global_load_lds_dwordx4 v[238:239], off
	v_lshl_add_u64 v[238:239], s[18:19], 0, v[2:3]
	s_mov_b32 m0, s42
	s_nop 0
	global_load_lds_dwordx4 v[238:239], off
	v_lshl_add_u64 v[238:239], s[18:19], 0, v[176:177]
	s_add_i32 m0, s42, 0x2000
	s_nop 0
	global_load_lds_dwordx4 v[238:239], off
	v_lshl_add_u64 v[238:239], v[242:243], 0, s[16:17]
	s_mov_b32 m0, s61
	s_nop 0
	global_load_lds_dwordx4 v[238:239], off
	v_lshl_add_u64 v[238:239], v[244:245], 0, s[16:17]
	s_mov_b32 m0, s62
	s_nop 0
	global_load_lds_dwordx4 v[238:239], off
	s_waitcnt vmcnt(8)
	s_waitcnt lgkmcnt(0)
	s_barrier
	s_setprio 1
	s_waitcnt lgkmcnt(0)
	v_mfma_f32_16x16x32_bf16 v[72:75], v[60:63], v[164:167], v[72:75]
	v_mfma_f32_16x16x32_bf16 v[68:71], v[76:79], v[164:167], v[68:71]
	v_mfma_f32_16x16x32_bf16 v[52:55], v[60:63], v[190:193], v[52:55]
	v_mfma_f32_16x16x32_bf16 v[48:51], v[76:79], v[190:193], v[48:51]
	v_mfma_f32_16x16x32_bf16 v[32:35], v[60:63], v[198:201], v[32:35]
	v_mfma_f32_16x16x32_bf16 v[28:31], v[76:79], v[198:201], v[28:31]
	v_mfma_f32_16x16x32_bf16 v[16:19], v[60:63], v[206:209], v[16:19]
	v_mfma_f32_16x16x32_bf16 v[12:15], v[76:79], v[206:209], v[12:15]
	v_mfma_f32_16x16x32_bf16 v[72:75], v[64:67], v[186:189], v[72:75]
	v_mfma_f32_16x16x32_bf16 v[68:71], v[96:99], v[186:189], v[68:71]
	v_mfma_f32_16x16x32_bf16 v[52:55], v[64:67], v[194:197], v[52:55]
	v_mfma_f32_16x16x32_bf16 v[48:51], v[96:99], v[194:197], v[48:51]
	v_mfma_f32_16x16x32_bf16 v[32:35], v[64:67], v[202:205], v[32:35]
	v_mfma_f32_16x16x32_bf16 v[28:31], v[96:99], v[202:205], v[28:31]
	v_mfma_f32_16x16x32_bf16 v[16:19], v[64:67], v[210:213], v[16:19]
	v_mfma_f32_16x16x32_bf16 v[12:15], v[96:99], v[210:213], v[12:15]
	s_setprio 0
	s_setprio 1
	v_mfma_f32_16x16x32_bf16 v[44:47], v[116:119], v[164:167], v[44:47]
	v_mfma_f32_16x16x32_bf16 v[60:63], v[136:139], v[186:189], v[44:47]
	v_mfma_f32_16x16x32_bf16 v[44:47], v[156:159], v[164:167], v[56:59]
	v_mfma_f32_16x16x32_bf16 v[40:43], v[116:119], v[190:193], v[40:43]
	v_mfma_f32_16x16x32_bf16 v[36:39], v[156:159], v[190:193], v[36:39]
	v_mfma_f32_16x16x32_bf16 v[24:27], v[116:119], v[198:201], v[24:27]
	v_mfma_f32_16x16x32_bf16 v[20:23], v[156:159], v[198:201], v[20:23]
	v_mfma_f32_16x16x32_bf16 v[8:11], v[116:119], v[206:209], v[8:11]
	v_mfma_f32_16x16x32_bf16 v[4:7], v[156:159], v[206:209], v[4:7]
	v_mfma_f32_16x16x32_bf16 v[56:59], v[160:163], v[186:189], v[44:47]
	v_mfma_f32_16x16x32_bf16 v[40:43], v[136:139], v[194:197], v[40:43]
	v_mfma_f32_16x16x32_bf16 v[36:39], v[160:163], v[194:197], v[36:39]
	v_mfma_f32_16x16x32_bf16 v[24:27], v[136:139], v[202:205], v[24:27]
	v_mfma_f32_16x16x32_bf16 v[20:23], v[160:163], v[202:205], v[20:23]
	v_mfma_f32_16x16x32_bf16 v[8:11], v[136:139], v[210:213], v[8:11]
	v_mfma_f32_16x16x32_bf16 v[4:7], v[160:163], v[210:213], v[4:7]
	s_setprio 0
	s_barrier
	s_add_i32 s67, s67, 2
	s_add_u32 s4, s4, 0x100
	s_addc_u32 s5, s5, 0
	s_add_u32 s65, s65, 0x100
	s_addc_u32 s66, s66, 0
	s_cmp_gt_u32 s67, 13
	s_cbranch_scc0 .LBB0_93
	s_and_b64 vcc, exec, s[28:29]
	s_cbranch_vccz .LBB0_96
	s_barrier

.LBB0_198:
	v_readlane_b32 s74, v255, 62
	v_readlane_b32 s75, v252, 5
	s_nop 3
	s_cmp_eq_u32 s74, 0
	s_cbranch_scc1 .Learly_a_done
	s_cmp_lt_u32 s75, 64
	s_cbranch_scc1 .Learly_a_done
	s_mov_b64 s[76:77], exec
	v_readlane_b32 s78, v252, 11
	v_readlane_b32 s79, v252, 12
	s_nop 3
	s_and_b64 s[78:79], s[76:77], s[78:79]
	s_mov_b64 exec, s[78:79]
	s_cbranch_execz .Learly_a_rest
	v_readlane_b32 s80, v253, 26
	v_readlane_b32 s81, v253, 27
	s_nop 3
	s_add_u32 s80, s80, 0x2300
	s_addc_u32 s81, s81, 0
	v_mov_b32_e32 v1, 1
	s_nop 1
	global_atomic_add v3, v1, s[80:81]
